# 32x32x16 selected-block stream with exp work rebalanced between the QK and PV phases
# baseline (speedup 1.0000x reference)
.Lattn_it0:
	s_waitcnt vmcnt(4) lgkmcnt(0)
	s_barrier
	s_add_i32 s46, s38, 4
	s_min_u32 s46, s46, s48
	s_lshl_b32 s42, s46, 14
	s_add_i32 s47, s38, 2
	s_min_u32 s47, s47, s48
	s_lshl_b32 s44, s47, 7
	v_lshl_add_u64 v[160:161], s[42:43], 0, v[106:107]
	v_lshl_add_u64 v[208:209], s[44:45], 0, v[122:123]
	v_mfma_f32_32x32x16_bf16 v[20:35], v[204:207], v[244:247], 0
	v_cvt_pk_bf16_f32 v36, v68, v69
	v_add_f32_e32 v174, v174, v68
	v_add_f32_e32 v193, v193, v132
	v_cvt_pk_bf16_f32 v37, v70, v71
	v_add_f32_e32 v174, v174, v69
	v_add_f32_e32 v193, v193, v133
	v_mfma_f32_32x32x16_bf16 v[52:67], v[204:207], v[244:247], 0
	v_cvt_pk_bf16_f32 v38, v72, v73
	v_add_f32_e32 v174, v174, v70
	v_add_f32_e32 v193, v193, v134
	v_cvt_pk_bf16_f32 v39, v74, v75
	v_add_f32_e32 v174, v174, v71
	v_add_f32_e32 v193, v193, v135
	v_mfma_f32_32x32x16_bf16 v[20:35], v[108:111], v[4:7], v[20:35]
	v_cvt_pk_bf16_f32 v84, v76, v77
	v_add_f32_e32 v174, v174, v72
	v_add_f32_e32 v193, v193, v136
	v_cvt_pk_bf16_f32 v85, v78, v79
	v_add_f32_e32 v174, v174, v73
	v_add_f32_e32 v193, v193, v137
	ds_read_b128 v[108:111], v97 offset:57344
	s_add_i32 m0, s40, 0x0
	s_nop 0
	global_load_lds_dwordx4 v[160:161], off
	v_mfma_f32_32x32x16_bf16 v[20:35], v[112:115], v[8:11], v[20:35]
	v_cvt_pk_bf16_f32 v86, v80, v81
	v_add_f32_e32 v174, v174, v74
	v_add_f32_e32 v193, v193, v138
	v_cvt_pk_bf16_f32 v87, v82, v83
	v_add_f32_e32 v174, v174, v75
	v_add_f32_e32 v193, v193, v139
	ds_read_b128 v[112:115], v97 offset:61440
	v_mfma_f32_32x32x16_bf16 v[20:35], v[116:119], v[12:15], v[20:35]
	v_cvt_pk_bf16_f32 v88, v132, v133
	v_add_f32_e32 v174, v174, v76
	v_add_f32_e32 v193, v193, v140
	v_cvt_pk_bf16_f32 v89, v134, v135
	v_add_f32_e32 v174, v174, v77
	v_add_f32_e32 v193, v193, v141
	ds_read_b128 v[116:119], v98 offset:57344
	s_add_i32 m0, s41, 0x4000
	s_nop 0
	global_load_lds_dwordx4 v[208:209], off
	v_mfma_f32_32x32x16_bf16 v[20:35], v[124:127], v[16:19], v[20:35]
	v_cvt_pk_bf16_f32 v90, v136, v137
	v_add_f32_e32 v174, v174, v78
	v_add_f32_e32 v193, v193, v142
	v_cvt_pk_bf16_f32 v91, v138, v139
	v_add_f32_e32 v174, v174, v79
	v_add_f32_e32 v193, v193, v143
	ds_read_b128 v[124:127], v98 offset:61440
	v_mfma_f32_32x32x16_bf16 v[52:67], v[148:151], v[4:7], v[52:67]
	v_cvt_pk_bf16_f32 v92, v140, v141
	v_add_f32_e32 v174, v174, v80
	v_add_f32_e32 v193, v193, v144
	ds_read_b128 v[148:151], v102 offset:57344
	v_mfma_f32_32x32x16_bf16 v[52:67], v[152:155], v[8:11], v[52:67]
	v_cvt_pk_bf16_f32 v93, v142, v143
	v_add_f32_e32 v174, v174, v81
	v_add_f32_e32 v193, v193, v145
	v_exp_f32_e32 v20, v20
	v_exp_f32_e32 v21, v21
	ds_read_b128 v[152:155], v102 offset:61440
	v_mfma_f32_32x32x16_bf16 v[52:67], v[156:159], v[12:15], v[52:67]
	v_cvt_pk_bf16_f32 v94, v144, v145
	v_add_f32_e32 v174, v174, v82
	v_add_f32_e32 v193, v193, v146
	v_exp_f32_e32 v22, v22
	v_exp_f32_e32 v23, v23
	ds_read_b128 v[156:159], v103 offset:57344
	v_mfma_f32_32x32x16_bf16 v[52:67], v[200:203], v[16:19], v[52:67]
	v_cvt_pk_bf16_f32 v95, v146, v147
	v_add_f32_e32 v174, v174, v83
	v_add_f32_e32 v193, v193, v147
	v_exp_f32_e32 v24, v24
	v_exp_f32_e32 v25, v25
	ds_read_b128 v[200:203], v103 offset:61440
	s_waitcnt lgkmcnt(7)
	v_mfma_f32_32x32x16_bf16 v[176:191], v[108:111], v[36:39], v[176:191]
	v_exp_f32_e32 v26, v26
	v_exp_f32_e32 v27, v27
	v_exp_f32_e32 v28, v28
	v_exp_f32_e32 v29, v29
	ds_read_b128 v[108:111], v40 offset:8192
	s_waitcnt lgkmcnt(7)
	v_mfma_f32_32x32x16_bf16 v[228:243], v[112:115], v[36:39], v[228:243]
	v_exp_f32_e32 v30, v30
	v_exp_f32_e32 v31, v31
	v_exp_f32_e32 v32, v32
	v_exp_f32_e32 v33, v33
	ds_read_b128 v[112:115], v41 offset:8192
	s_waitcnt lgkmcnt(7)
	v_mfma_f32_32x32x16_bf16 v[176:191], v[116:119], v[84:87], v[176:191]
	v_exp_f32_e32 v34, v34
	v_exp_f32_e32 v35, v35
	v_exp_f32_e32 v52, v52
	ds_read_b128 v[116:119], v42 offset:8192
	s_waitcnt lgkmcnt(7)
	v_mfma_f32_32x32x16_bf16 v[228:243], v[124:127], v[84:87], v[228:243]
	v_exp_f32_e32 v53, v53
	v_exp_f32_e32 v54, v54
	v_exp_f32_e32 v55, v55
	ds_read_b128 v[124:127], v96 offset:8192
	s_waitcnt lgkmcnt(7)
	v_mfma_f32_32x32x16_bf16 v[176:191], v[148:151], v[88:91], v[176:191]
	v_exp_f32_e32 v56, v56
	v_exp_f32_e32 v57, v57
	v_exp_f32_e32 v58, v58
	ds_read_b128 v[148:151], v40 offset:12288
	s_waitcnt lgkmcnt(7)
	v_mfma_f32_32x32x16_bf16 v[228:243], v[152:155], v[88:91], v[228:243]
	v_exp_f32_e32 v59, v59
	v_exp_f32_e32 v60, v60
	v_exp_f32_e32 v61, v61
	ds_read_b128 v[152:155], v41 offset:12288
	s_waitcnt lgkmcnt(7)
	v_mfma_f32_32x32x16_bf16 v[176:191], v[156:159], v[92:95], v[176:191]
	v_exp_f32_e32 v62, v62
	v_exp_f32_e32 v63, v63
	v_exp_f32_e32 v64, v64
	ds_read_b128 v[156:159], v42 offset:12288
	s_waitcnt lgkmcnt(7)
	v_mfma_f32_32x32x16_bf16 v[228:243], v[200:203], v[92:95], v[228:243]
	v_exp_f32_e32 v65, v65
	v_exp_f32_e32 v66, v66
	v_exp_f32_e32 v67, v67
	ds_read_b128 v[200:203], v96 offset:12288
	s_cmp_eq_u32 s38, s48
	s_cbranch_scc0 .Lattn_nofix0
	v_cmp_le_i32_e64 s[50:51], 0, v120
	v_cmp_le_i32_e64 s[52:53], 1, v120
	v_cmp_le_i32_e64 s[56:57], 2, v120
	v_cndmask_b32_e64 v20, 0, v20, s[50:51]
	v_cmp_le_i32_e64 s[50:51], 3, v120
	v_cndmask_b32_e64 v21, 0, v21, s[52:53]
	v_cmp_le_i32_e64 s[52:53], 4, v120
	v_cndmask_b32_e64 v22, 0, v22, s[56:57]
	v_cmp_le_i32_e64 s[56:57], 5, v120
	v_cndmask_b32_e64 v23, 0, v23, s[50:51]
	v_cmp_le_i32_e64 s[50:51], 6, v120
	v_cndmask_b32_e64 v24, 0, v24, s[52:53]
	v_cmp_le_i32_e64 s[52:53], 7, v120
	v_cndmask_b32_e64 v25, 0, v25, s[56:57]
	v_cmp_le_i32_e64 s[56:57], 16, v120
	v_cndmask_b32_e64 v26, 0, v26, s[50:51]
	v_cmp_le_i32_e64 s[50:51], 17, v120
	v_cndmask_b32_e64 v27, 0, v27, s[52:53]
	v_cmp_le_i32_e64 s[52:53], 18, v120
	v_cndmask_b32_e64 v28, 0, v28, s[56:57]
	v_cmp_le_i32_e64 s[56:57], 19, v120
	v_cndmask_b32_e64 v29, 0, v29, s[50:51]
	v_cmp_le_i32_e64 s[50:51], 20, v120
	v_cndmask_b32_e64 v30, 0, v30, s[52:53]
	v_cmp_le_i32_e64 s[52:53], 21, v120
	v_cndmask_b32_e64 v31, 0, v31, s[56:57]
	v_cmp_le_i32_e64 s[56:57], 22, v120
	v_cndmask_b32_e64 v32, 0, v32, s[50:51]
	v_cmp_le_i32_e64 s[50:51], 23, v120
	v_cndmask_b32_e64 v33, 0, v33, s[52:53]
	v_cmp_le_i32_e64 s[52:53], 32, v120
	v_cndmask_b32_e64 v34, 0, v34, s[56:57]
	v_cmp_le_i32_e64 s[56:57], 33, v120
	v_cndmask_b32_e64 v35, 0, v35, s[50:51]
	v_cmp_le_i32_e64 s[50:51], 34, v120
	v_cndmask_b32_e64 v52, 0, v52, s[52:53]
	v_cmp_le_i32_e64 s[52:53], 35, v120
	v_cndmask_b32_e64 v53, 0, v53, s[56:57]
	v_cmp_le_i32_e64 s[56:57], 36, v120
	v_cndmask_b32_e64 v54, 0, v54, s[50:51]
	v_cmp_le_i32_e64 s[50:51], 37, v120
	v_cndmask_b32_e64 v55, 0, v55, s[52:53]
	v_cmp_le_i32_e64 s[52:53], 38, v120
	v_cndmask_b32_e64 v56, 0, v56, s[56:57]
	v_cmp_le_i32_e64 s[56:57], 39, v120
	v_cndmask_b32_e64 v57, 0, v57, s[50:51]
	v_cmp_le_i32_e64 s[50:51], 48, v120
	v_cndmask_b32_e64 v58, 0, v58, s[52:53]
	v_cmp_le_i32_e64 s[52:53], 49, v120
	v_cndmask_b32_e64 v59, 0, v59, s[56:57]
	v_cmp_le_i32_e64 s[56:57], 50, v120
	v_cndmask_b32_e64 v60, 0, v60, s[50:51]
	v_cmp_le_i32_e64 s[50:51], 51, v120
	v_cndmask_b32_e64 v61, 0, v61, s[52:53]
	v_cmp_le_i32_e64 s[52:53], 52, v120
	v_cndmask_b32_e64 v62, 0, v62, s[56:57]
	v_cmp_le_i32_e64 s[56:57], 53, v120
	v_cndmask_b32_e64 v63, 0, v63, s[50:51]
	v_cmp_le_i32_e64 s[50:51], 54, v120
	v_cndmask_b32_e64 v64, 0, v64, s[52:53]
	v_cmp_le_i32_e64 s[52:53], 55, v120
	v_cndmask_b32_e64 v65, 0, v65, s[56:57]
	s_nop 0
	v_cndmask_b32_e64 v66, 0, v66, s[50:51]
	s_nop 0
	v_cndmask_b32_e64 v67, 0, v67, s[52:53]
	s_nop 0

.Lattn_it1:
	s_waitcnt vmcnt(4) lgkmcnt(0)
	s_barrier
	s_add_i32 s46, s38, 4
	s_min_u32 s46, s46, s48
	s_lshl_b32 s42, s46, 14
	s_add_i32 s47, s38, 2
	s_min_u32 s47, s47, s48
	s_lshl_b32 s44, s47, 7
	v_lshl_add_u64 v[160:161], s[42:43], 0, v[106:107]
	v_lshl_add_u64 v[208:209], s[44:45], 0, v[122:123]
	v_mfma_f32_32x32x16_bf16 v[68:83], v[204:207], v[244:247], 0
	v_cvt_pk_bf16_f32 v36, v20, v21
	v_add_f32_e32 v174, v174, v20
	v_add_f32_e32 v193, v193, v52
	v_cvt_pk_bf16_f32 v37, v22, v23
	v_add_f32_e32 v174, v174, v21
	v_add_f32_e32 v193, v193, v53
	v_mfma_f32_32x32x16_bf16 v[132:147], v[204:207], v[244:247], 0
	v_cvt_pk_bf16_f32 v38, v24, v25
	v_add_f32_e32 v174, v174, v22
	v_add_f32_e32 v193, v193, v54
	v_cvt_pk_bf16_f32 v39, v26, v27
	v_add_f32_e32 v174, v174, v23
	v_add_f32_e32 v193, v193, v55
	v_mfma_f32_32x32x16_bf16 v[68:83], v[108:111], v[4:7], v[68:83]
	v_cvt_pk_bf16_f32 v84, v28, v29
	v_add_f32_e32 v174, v174, v24
	v_add_f32_e32 v193, v193, v56
	v_cvt_pk_bf16_f32 v85, v30, v31
	v_add_f32_e32 v174, v174, v25
	v_add_f32_e32 v193, v193, v57
	ds_read_b128 v[108:111], v97 offset:32768
	s_add_i32 m0, s40, 0x2000
	s_nop 0
	global_load_lds_dwordx4 v[160:161], off
	v_mfma_f32_32x32x16_bf16 v[68:83], v[112:115], v[8:11], v[68:83]
	v_cvt_pk_bf16_f32 v86, v32, v33
	v_add_f32_e32 v174, v174, v26
	v_add_f32_e32 v193, v193, v58
	v_cvt_pk_bf16_f32 v87, v34, v35
	v_add_f32_e32 v174, v174, v27
	v_add_f32_e32 v193, v193, v59
	ds_read_b128 v[112:115], v97 offset:36864
	v_mfma_f32_32x32x16_bf16 v[68:83], v[116:119], v[12:15], v[68:83]
	v_cvt_pk_bf16_f32 v88, v52, v53
	v_add_f32_e32 v174, v174, v28
	v_add_f32_e32 v193, v193, v60
	v_cvt_pk_bf16_f32 v89, v54, v55
	v_add_f32_e32 v174, v174, v29
	v_add_f32_e32 v193, v193, v61
	ds_read_b128 v[116:119], v98 offset:32768
	s_add_i32 m0, s41, 0x6000
	s_nop 0
	global_load_lds_dwordx4 v[208:209], off
	v_mfma_f32_32x32x16_bf16 v[68:83], v[124:127], v[16:19], v[68:83]
	v_cvt_pk_bf16_f32 v90, v56, v57
	v_add_f32_e32 v174, v174, v30
	v_add_f32_e32 v193, v193, v62
	v_cvt_pk_bf16_f32 v91, v58, v59
	v_add_f32_e32 v174, v174, v31
	v_add_f32_e32 v193, v193, v63
	ds_read_b128 v[124:127], v98 offset:36864
	v_mfma_f32_32x32x16_bf16 v[132:147], v[148:151], v[4:7], v[132:147]
	v_cvt_pk_bf16_f32 v92, v60, v61
	v_add_f32_e32 v174, v174, v32
	v_add_f32_e32 v193, v193, v64
	ds_read_b128 v[148:151], v102 offset:32768
	v_mfma_f32_32x32x16_bf16 v[132:147], v[152:155], v[8:11], v[132:147]
	v_cvt_pk_bf16_f32 v93, v62, v63
	v_add_f32_e32 v174, v174, v33
	v_add_f32_e32 v193, v193, v65
	v_exp_f32_e32 v68, v68
	v_exp_f32_e32 v69, v69
	ds_read_b128 v[152:155], v102 offset:36864
	v_mfma_f32_32x32x16_bf16 v[132:147], v[156:159], v[12:15], v[132:147]
	v_cvt_pk_bf16_f32 v94, v64, v65
	v_add_f32_e32 v174, v174, v34
	v_add_f32_e32 v193, v193, v66
	v_exp_f32_e32 v70, v70
	v_exp_f32_e32 v71, v71
	ds_read_b128 v[156:159], v103 offset:32768
	v_mfma_f32_32x32x16_bf16 v[132:147], v[200:203], v[16:19], v[132:147]
	v_cvt_pk_bf16_f32 v95, v66, v67
	v_add_f32_e32 v174, v174, v35
	v_add_f32_e32 v193, v193, v67
	v_exp_f32_e32 v72, v72
	v_exp_f32_e32 v73, v73
	ds_read_b128 v[200:203], v103 offset:36864
	s_waitcnt lgkmcnt(7)
	v_mfma_f32_32x32x16_bf16 v[176:191], v[108:111], v[36:39], v[176:191]
	v_exp_f32_e32 v74, v74
	v_exp_f32_e32 v75, v75
	v_exp_f32_e32 v76, v76
	v_exp_f32_e32 v77, v77
	ds_read_b128 v[108:111], v40 offset:16384
	s_waitcnt lgkmcnt(7)
	v_mfma_f32_32x32x16_bf16 v[228:243], v[112:115], v[36:39], v[228:243]
	v_exp_f32_e32 v78, v78
	v_exp_f32_e32 v79, v79
	v_exp_f32_e32 v80, v80
	v_exp_f32_e32 v81, v81
	ds_read_b128 v[112:115], v41 offset:16384
	s_waitcnt lgkmcnt(7)
	v_mfma_f32_32x32x16_bf16 v[176:191], v[116:119], v[84:87], v[176:191]
	v_exp_f32_e32 v82, v82
	v_exp_f32_e32 v83, v83
	v_exp_f32_e32 v132, v132
	ds_read_b128 v[116:119], v42 offset:16384
	s_waitcnt lgkmcnt(7)
	v_mfma_f32_32x32x16_bf16 v[228:243], v[124:127], v[84:87], v[228:243]
	v_exp_f32_e32 v133, v133
	v_exp_f32_e32 v134, v134
	v_exp_f32_e32 v135, v135
	ds_read_b128 v[124:127], v96 offset:16384
	s_waitcnt lgkmcnt(7)
	v_mfma_f32_32x32x16_bf16 v[176:191], v[148:151], v[88:91], v[176:191]
	v_exp_f32_e32 v136, v136
	v_exp_f32_e32 v137, v137
	v_exp_f32_e32 v138, v138
	ds_read_b128 v[148:151], v40 offset:20480
	s_waitcnt lgkmcnt(7)
	v_mfma_f32_32x32x16_bf16 v[228:243], v[152:155], v[88:91], v[228:243]
	v_exp_f32_e32 v139, v139
	v_exp_f32_e32 v140, v140
	v_exp_f32_e32 v141, v141
	ds_read_b128 v[152:155], v41 offset:20480
	s_waitcnt lgkmcnt(7)
	v_mfma_f32_32x32x16_bf16 v[176:191], v[156:159], v[92:95], v[176:191]
	v_exp_f32_e32 v142, v142
	v_exp_f32_e32 v143, v143
	v_exp_f32_e32 v144, v144
	ds_read_b128 v[156:159], v42 offset:20480
	s_waitcnt lgkmcnt(7)
	v_mfma_f32_32x32x16_bf16 v[228:243], v[200:203], v[92:95], v[228:243]
	v_exp_f32_e32 v145, v145
	v_exp_f32_e32 v146, v146
	v_exp_f32_e32 v147, v147
	ds_read_b128 v[200:203], v96 offset:20480
	s_cmp_eq_u32 s38, s48
	s_cbranch_scc0 .Lattn_nofix1
	v_cmp_le_i32_e64 s[50:51], 0, v120
	v_cmp_le_i32_e64 s[52:53], 1, v120
	v_cmp_le_i32_e64 s[56:57], 2, v120
	v_cndmask_b32_e64 v68, 0, v68, s[50:51]
	v_cmp_le_i32_e64 s[50:51], 3, v120
	v_cndmask_b32_e64 v69, 0, v69, s[52:53]
	v_cmp_le_i32_e64 s[52:53], 4, v120
	v_cndmask_b32_e64 v70, 0, v70, s[56:57]
	v_cmp_le_i32_e64 s[56:57], 5, v120
	v_cndmask_b32_e64 v71, 0, v71, s[50:51]
	v_cmp_le_i32_e64 s[50:51], 6, v120
	v_cndmask_b32_e64 v72, 0, v72, s[52:53]
	v_cmp_le_i32_e64 s[52:53], 7, v120
	v_cndmask_b32_e64 v73, 0, v73, s[56:57]
	v_cmp_le_i32_e64 s[56:57], 16, v120
	v_cndmask_b32_e64 v74, 0, v74, s[50:51]
	v_cmp_le_i32_e64 s[50:51], 17, v120
	v_cndmask_b32_e64 v75, 0, v75, s[52:53]
	v_cmp_le_i32_e64 s[52:53], 18, v120
	v_cndmask_b32_e64 v76, 0, v76, s[56:57]
	v_cmp_le_i32_e64 s[56:57], 19, v120
	v_cndmask_b32_e64 v77, 0, v77, s[50:51]
	v_cmp_le_i32_e64 s[50:51], 20, v120
	v_cndmask_b32_e64 v78, 0, v78, s[52:53]
	v_cmp_le_i32_e64 s[52:53], 21, v120
	v_cndmask_b32_e64 v79, 0, v79, s[56:57]
	v_cmp_le_i32_e64 s[56:57], 22, v120
	v_cndmask_b32_e64 v80, 0, v80, s[50:51]
	v_cmp_le_i32_e64 s[50:51], 23, v120
	v_cndmask_b32_e64 v81, 0, v81, s[52:53]
	v_cmp_le_i32_e64 s[52:53], 32, v120
	v_cndmask_b32_e64 v82, 0, v82, s[56:57]
	v_cmp_le_i32_e64 s[56:57], 33, v120
	v_cndmask_b32_e64 v83, 0, v83, s[50:51]
	v_cmp_le_i32_e64 s[50:51], 34, v120
	v_cndmask_b32_e64 v132, 0, v132, s[52:53]
	v_cmp_le_i32_e64 s[52:53], 35, v120
	v_cndmask_b32_e64 v133, 0, v133, s[56:57]
	v_cmp_le_i32_e64 s[56:57], 36, v120
	v_cndmask_b32_e64 v134, 0, v134, s[50:51]
	v_cmp_le_i32_e64 s[50:51], 37, v120
	v_cndmask_b32_e64 v135, 0, v135, s[52:53]
	v_cmp_le_i32_e64 s[52:53], 38, v120
	v_cndmask_b32_e64 v136, 0, v136, s[56:57]
	v_cmp_le_i32_e64 s[56:57], 39, v120
	v_cndmask_b32_e64 v137, 0, v137, s[50:51]
	v_cmp_le_i32_e64 s[50:51], 48, v120
	v_cndmask_b32_e64 v138, 0, v138, s[52:53]
	v_cmp_le_i32_e64 s[52:53], 49, v120
	v_cndmask_b32_e64 v139, 0, v139, s[56:57]
	v_cmp_le_i32_e64 s[56:57], 50, v120
	v_cndmask_b32_e64 v140, 0, v140, s[50:51]
	v_cmp_le_i32_e64 s[50:51], 51, v120
	v_cndmask_b32_e64 v141, 0, v141, s[52:53]
	v_cmp_le_i32_e64 s[52:53], 52, v120
	v_cndmask_b32_e64 v142, 0, v142, s[56:57]
	v_cmp_le_i32_e64 s[56:57], 53, v120
	v_cndmask_b32_e64 v143, 0, v143, s[50:51]
	v_cmp_le_i32_e64 s[50:51], 54, v120
	v_cndmask_b32_e64 v144, 0, v144, s[52:53]
	v_cmp_le_i32_e64 s[52:53], 55, v120
	v_cndmask_b32_e64 v145, 0, v145, s[56:57]
	s_nop 0
	v_cndmask_b32_e64 v146, 0, v146, s[50:51]
	s_nop 0
	v_cndmask_b32_e64 v147, 0, v147, s[52:53]
	s_nop 0

.Lattn_it2:
	s_waitcnt vmcnt(4) lgkmcnt(0)
	s_barrier
	s_add_i32 s46, s38, 4
	s_min_u32 s46, s46, s48
	s_lshl_b32 s42, s46, 14
	s_add_i32 s47, s38, 2
	s_min_u32 s47, s47, s48
	s_lshl_b32 s44, s47, 7
	v_lshl_add_u64 v[160:161], s[42:43], 0, v[106:107]
	v_lshl_add_u64 v[208:209], s[44:45], 0, v[122:123]
	v_mfma_f32_32x32x16_bf16 v[20:35], v[204:207], v[244:247], 0
	v_cvt_pk_bf16_f32 v36, v68, v69
	v_add_f32_e32 v174, v174, v68
	v_add_f32_e32 v193, v193, v132
	v_cvt_pk_bf16_f32 v37, v70, v71
	v_add_f32_e32 v174, v174, v69
	v_add_f32_e32 v193, v193, v133
	v_mfma_f32_32x32x16_bf16 v[52:67], v[204:207], v[244:247], 0
	v_cvt_pk_bf16_f32 v38, v72, v73
	v_add_f32_e32 v174, v174, v70
	v_add_f32_e32 v193, v193, v134
	v_cvt_pk_bf16_f32 v39, v74, v75
	v_add_f32_e32 v174, v174, v71
	v_add_f32_e32 v193, v193, v135
	v_mfma_f32_32x32x16_bf16 v[20:35], v[108:111], v[4:7], v[20:35]
	v_cvt_pk_bf16_f32 v84, v76, v77
	v_add_f32_e32 v174, v174, v72
	v_add_f32_e32 v193, v193, v136
	v_cvt_pk_bf16_f32 v85, v78, v79
	v_add_f32_e32 v174, v174, v73
	v_add_f32_e32 v193, v193, v137
	ds_read_b128 v[108:111], v97 offset:40960
	s_add_i32 m0, s40, 0x4000
	s_nop 0
	global_load_lds_dwordx4 v[160:161], off
	v_mfma_f32_32x32x16_bf16 v[20:35], v[112:115], v[8:11], v[20:35]
	v_cvt_pk_bf16_f32 v86, v80, v81
	v_add_f32_e32 v174, v174, v74
	v_add_f32_e32 v193, v193, v138
	v_cvt_pk_bf16_f32 v87, v82, v83
	v_add_f32_e32 v174, v174, v75
	v_add_f32_e32 v193, v193, v139
	ds_read_b128 v[112:115], v97 offset:45056
	v_mfma_f32_32x32x16_bf16 v[20:35], v[116:119], v[12:15], v[20:35]
	v_cvt_pk_bf16_f32 v88, v132, v133
	v_add_f32_e32 v174, v174, v76
	v_add_f32_e32 v193, v193, v140
	v_cvt_pk_bf16_f32 v89, v134, v135
	v_add_f32_e32 v174, v174, v77
	v_add_f32_e32 v193, v193, v141
	ds_read_b128 v[116:119], v98 offset:40960
	s_add_i32 m0, s41, 0x0
	s_nop 0
	global_load_lds_dwordx4 v[208:209], off
	v_mfma_f32_32x32x16_bf16 v[20:35], v[124:127], v[16:19], v[20:35]
	v_cvt_pk_bf16_f32 v90, v136, v137
	v_add_f32_e32 v174, v174, v78
	v_add_f32_e32 v193, v193, v142
	v_cvt_pk_bf16_f32 v91, v138, v139
	v_add_f32_e32 v174, v174, v79
	v_add_f32_e32 v193, v193, v143
	ds_read_b128 v[124:127], v98 offset:45056
	v_mfma_f32_32x32x16_bf16 v[52:67], v[148:151], v[4:7], v[52:67]
	v_cvt_pk_bf16_f32 v92, v140, v141
	v_add_f32_e32 v174, v174, v80
	v_add_f32_e32 v193, v193, v144
	ds_read_b128 v[148:151], v102 offset:40960
	v_mfma_f32_32x32x16_bf16 v[52:67], v[152:155], v[8:11], v[52:67]
	v_cvt_pk_bf16_f32 v93, v142, v143
	v_add_f32_e32 v174, v174, v81
	v_add_f32_e32 v193, v193, v145
	v_exp_f32_e32 v20, v20
	v_exp_f32_e32 v21, v21
	ds_read_b128 v[152:155], v102 offset:45056
	v_mfma_f32_32x32x16_bf16 v[52:67], v[156:159], v[12:15], v[52:67]
	v_cvt_pk_bf16_f32 v94, v144, v145
	v_add_f32_e32 v174, v174, v82
	v_add_f32_e32 v193, v193, v146
	v_exp_f32_e32 v22, v22
	v_exp_f32_e32 v23, v23
	ds_read_b128 v[156:159], v103 offset:40960
	v_mfma_f32_32x32x16_bf16 v[52:67], v[200:203], v[16:19], v[52:67]
	v_cvt_pk_bf16_f32 v95, v146, v147
	v_add_f32_e32 v174, v174, v83
	v_add_f32_e32 v193, v193, v147
	v_exp_f32_e32 v24, v24
	v_exp_f32_e32 v25, v25
	ds_read_b128 v[200:203], v103 offset:45056
	s_waitcnt lgkmcnt(7)
	v_mfma_f32_32x32x16_bf16 v[176:191], v[108:111], v[36:39], v[176:191]
	v_exp_f32_e32 v26, v26
	v_exp_f32_e32 v27, v27
	v_exp_f32_e32 v28, v28
	v_exp_f32_e32 v29, v29
	ds_read_b128 v[108:111], v40 offset:24576
	s_waitcnt lgkmcnt(7)
	v_mfma_f32_32x32x16_bf16 v[228:243], v[112:115], v[36:39], v[228:243]
	v_exp_f32_e32 v30, v30
	v_exp_f32_e32 v31, v31
	v_exp_f32_e32 v32, v32
	v_exp_f32_e32 v33, v33
	ds_read_b128 v[112:115], v41 offset:24576
	s_waitcnt lgkmcnt(7)
	v_mfma_f32_32x32x16_bf16 v[176:191], v[116:119], v[84:87], v[176:191]
	v_exp_f32_e32 v34, v34
	v_exp_f32_e32 v35, v35
	v_exp_f32_e32 v52, v52
	ds_read_b128 v[116:119], v42 offset:24576
	s_waitcnt lgkmcnt(7)
	v_mfma_f32_32x32x16_bf16 v[228:243], v[124:127], v[84:87], v[228:243]
	v_exp_f32_e32 v53, v53
	v_exp_f32_e32 v54, v54
	v_exp_f32_e32 v55, v55
	ds_read_b128 v[124:127], v96 offset:24576
	s_waitcnt lgkmcnt(7)
	v_mfma_f32_32x32x16_bf16 v[176:191], v[148:151], v[88:91], v[176:191]
	v_exp_f32_e32 v56, v56
	v_exp_f32_e32 v57, v57
	v_exp_f32_e32 v58, v58
	ds_read_b128 v[148:151], v40 offset:28672
	s_waitcnt lgkmcnt(7)
	v_mfma_f32_32x32x16_bf16 v[228:243], v[152:155], v[88:91], v[228:243]
	v_exp_f32_e32 v59, v59
	v_exp_f32_e32 v60, v60
	v_exp_f32_e32 v61, v61
	ds_read_b128 v[152:155], v41 offset:28672
	s_waitcnt lgkmcnt(7)
	v_mfma_f32_32x32x16_bf16 v[176:191], v[156:159], v[92:95], v[176:191]
	v_exp_f32_e32 v62, v62
	v_exp_f32_e32 v63, v63
	v_exp_f32_e32 v64, v64
	ds_read_b128 v[156:159], v42 offset:28672
	s_waitcnt lgkmcnt(7)
	v_mfma_f32_32x32x16_bf16 v[228:243], v[200:203], v[92:95], v[228:243]
	v_exp_f32_e32 v65, v65
	v_exp_f32_e32 v66, v66
	v_exp_f32_e32 v67, v67
	ds_read_b128 v[200:203], v96 offset:28672
	s_cmp_eq_u32 s38, s48
	s_cbranch_scc0 .Lattn_nofix2
	v_cmp_le_i32_e64 s[50:51], 0, v120
	v_cmp_le_i32_e64 s[52:53], 1, v120
	v_cmp_le_i32_e64 s[56:57], 2, v120
	v_cndmask_b32_e64 v20, 0, v20, s[50:51]
	v_cmp_le_i32_e64 s[50:51], 3, v120
	v_cndmask_b32_e64 v21, 0, v21, s[52:53]
	v_cmp_le_i32_e64 s[52:53], 4, v120
	v_cndmask_b32_e64 v22, 0, v22, s[56:57]
	v_cmp_le_i32_e64 s[56:57], 5, v120
	v_cndmask_b32_e64 v23, 0, v23, s[50:51]
	v_cmp_le_i32_e64 s[50:51], 6, v120
	v_cndmask_b32_e64 v24, 0, v24, s[52:53]
	v_cmp_le_i32_e64 s[52:53], 7, v120
	v_cndmask_b32_e64 v25, 0, v25, s[56:57]
	v_cmp_le_i32_e64 s[56:57], 16, v120
	v_cndmask_b32_e64 v26, 0, v26, s[50:51]
	v_cmp_le_i32_e64 s[50:51], 17, v120
	v_cndmask_b32_e64 v27, 0, v27, s[52:53]
	v_cmp_le_i32_e64 s[52:53], 18, v120
	v_cndmask_b32_e64 v28, 0, v28, s[56:57]
	v_cmp_le_i32_e64 s[56:57], 19, v120
	v_cndmask_b32_e64 v29, 0, v29, s[50:51]
	v_cmp_le_i32_e64 s[50:51], 20, v120
	v_cndmask_b32_e64 v30, 0, v30, s[52:53]
	v_cmp_le_i32_e64 s[52:53], 21, v120
	v_cndmask_b32_e64 v31, 0, v31, s[56:57]
	v_cmp_le_i32_e64 s[56:57], 22, v120
	v_cndmask_b32_e64 v32, 0, v32, s[50:51]
	v_cmp_le_i32_e64 s[50:51], 23, v120
	v_cndmask_b32_e64 v33, 0, v33, s[52:53]
	v_cmp_le_i32_e64 s[52:53], 32, v120
	v_cndmask_b32_e64 v34, 0, v34, s[56:57]
	v_cmp_le_i32_e64 s[56:57], 33, v120
	v_cndmask_b32_e64 v35, 0, v35, s[50:51]
	v_cmp_le_i32_e64 s[50:51], 34, v120
	v_cndmask_b32_e64 v52, 0, v52, s[52:53]
	v_cmp_le_i32_e64 s[52:53], 35, v120
	v_cndmask_b32_e64 v53, 0, v53, s[56:57]
	v_cmp_le_i32_e64 s[56:57], 36, v120
	v_cndmask_b32_e64 v54, 0, v54, s[50:51]
	v_cmp_le_i32_e64 s[50:51], 37, v120
	v_cndmask_b32_e64 v55, 0, v55, s[52:53]
	v_cmp_le_i32_e64 s[52:53], 38, v120
	v_cndmask_b32_e64 v56, 0, v56, s[56:57]
	v_cmp_le_i32_e64 s[56:57], 39, v120
	v_cndmask_b32_e64 v57, 0, v57, s[50:51]
	v_cmp_le_i32_e64 s[50:51], 48, v120
	v_cndmask_b32_e64 v58, 0, v58, s[52:53]
	v_cmp_le_i32_e64 s[52:53], 49, v120
	v_cndmask_b32_e64 v59, 0, v59, s[56:57]
	v_cmp_le_i32_e64 s[56:57], 50, v120
	v_cndmask_b32_e64 v60, 0, v60, s[50:51]
	v_cmp_le_i32_e64 s[50:51], 51, v120
	v_cndmask_b32_e64 v61, 0, v61, s[52:53]
	v_cmp_le_i32_e64 s[52:53], 52, v120
	v_cndmask_b32_e64 v62, 0, v62, s[56:57]
	v_cmp_le_i32_e64 s[56:57], 53, v120
	v_cndmask_b32_e64 v63, 0, v63, s[50:51]
	v_cmp_le_i32_e64 s[50:51], 54, v120
	v_cndmask_b32_e64 v64, 0, v64, s[52:53]
	v_cmp_le_i32_e64 s[52:53], 55, v120
	v_cndmask_b32_e64 v65, 0, v65, s[56:57]
	s_nop 0
	v_cndmask_b32_e64 v66, 0, v66, s[50:51]
	s_nop 0
	v_cndmask_b32_e64 v67, 0, v67, s[52:53]
	s_nop 0

.Lattn_it3:
	s_waitcnt vmcnt(4) lgkmcnt(0)
	s_barrier
	s_add_i32 s46, s38, 4
	s_min_u32 s46, s46, s48
	s_lshl_b32 s42, s46, 14
	s_add_i32 s47, s38, 2
	s_min_u32 s47, s47, s48
	s_lshl_b32 s44, s47, 7
	v_lshl_add_u64 v[160:161], s[42:43], 0, v[106:107]
	v_lshl_add_u64 v[208:209], s[44:45], 0, v[122:123]
	v_mfma_f32_32x32x16_bf16 v[68:83], v[204:207], v[244:247], 0
	v_cvt_pk_bf16_f32 v36, v20, v21
	v_add_f32_e32 v174, v174, v20
	v_add_f32_e32 v193, v193, v52
	v_cvt_pk_bf16_f32 v37, v22, v23
	v_add_f32_e32 v174, v174, v21
	v_add_f32_e32 v193, v193, v53
	v_mfma_f32_32x32x16_bf16 v[132:147], v[204:207], v[244:247], 0
	v_cvt_pk_bf16_f32 v38, v24, v25
	v_add_f32_e32 v174, v174, v22
	v_add_f32_e32 v193, v193, v54
	v_cvt_pk_bf16_f32 v39, v26, v27
	v_add_f32_e32 v174, v174, v23
	v_add_f32_e32 v193, v193, v55
	v_mfma_f32_32x32x16_bf16 v[68:83], v[108:111], v[4:7], v[68:83]
	v_cvt_pk_bf16_f32 v84, v28, v29
	v_add_f32_e32 v174, v174, v24
	v_add_f32_e32 v193, v193, v56
	v_cvt_pk_bf16_f32 v85, v30, v31
	v_add_f32_e32 v174, v174, v25
	v_add_f32_e32 v193, v193, v57
	ds_read_b128 v[108:111], v97 offset:49152
	s_add_i32 m0, s40, 0x6000
	s_nop 0
	global_load_lds_dwordx4 v[160:161], off
	v_mfma_f32_32x32x16_bf16 v[68:83], v[112:115], v[8:11], v[68:83]
	v_cvt_pk_bf16_f32 v86, v32, v33
	v_add_f32_e32 v174, v174, v26
	v_add_f32_e32 v193, v193, v58
	v_cvt_pk_bf16_f32 v87, v34, v35
	v_add_f32_e32 v174, v174, v27
	v_add_f32_e32 v193, v193, v59
	ds_read_b128 v[112:115], v97 offset:53248
	v_mfma_f32_32x32x16_bf16 v[68:83], v[116:119], v[12:15], v[68:83]
	v_cvt_pk_bf16_f32 v88, v52, v53
	v_add_f32_e32 v174, v174, v28
	v_add_f32_e32 v193, v193, v60
	v_cvt_pk_bf16_f32 v89, v54, v55
	v_add_f32_e32 v174, v174, v29
	v_add_f32_e32 v193, v193, v61
	ds_read_b128 v[116:119], v98 offset:49152
	s_add_i32 m0, s41, 0x2000
	s_nop 0
	global_load_lds_dwordx4 v[208:209], off
	v_mfma_f32_32x32x16_bf16 v[68:83], v[124:127], v[16:19], v[68:83]
	v_cvt_pk_bf16_f32 v90, v56, v57
	v_add_f32_e32 v174, v174, v30
	v_add_f32_e32 v193, v193, v62
	v_cvt_pk_bf16_f32 v91, v58, v59
	v_add_f32_e32 v174, v174, v31
	v_add_f32_e32 v193, v193, v63
	ds_read_b128 v[124:127], v98 offset:53248
	v_mfma_f32_32x32x16_bf16 v[132:147], v[148:151], v[4:7], v[132:147]
	v_cvt_pk_bf16_f32 v92, v60, v61
	v_add_f32_e32 v174, v174, v32
	v_add_f32_e32 v193, v193, v64
	ds_read_b128 v[148:151], v102 offset:49152
	v_mfma_f32_32x32x16_bf16 v[132:147], v[152:155], v[8:11], v[132:147]
	v_cvt_pk_bf16_f32 v93, v62, v63
	v_add_f32_e32 v174, v174, v33
	v_add_f32_e32 v193, v193, v65
	v_exp_f32_e32 v68, v68
	v_exp_f32_e32 v69, v69
	ds_read_b128 v[152:155], v102 offset:53248
	v_mfma_f32_32x32x16_bf16 v[132:147], v[156:159], v[12:15], v[132:147]
	v_cvt_pk_bf16_f32 v94, v64, v65
	v_add_f32_e32 v174, v174, v34
	v_add_f32_e32 v193, v193, v66
	v_exp_f32_e32 v70, v70
	v_exp_f32_e32 v71, v71
	ds_read_b128 v[156:159], v103 offset:49152
	v_mfma_f32_32x32x16_bf16 v[132:147], v[200:203], v[16:19], v[132:147]
	v_cvt_pk_bf16_f32 v95, v66, v67
	v_add_f32_e32 v174, v174, v35
	v_add_f32_e32 v193, v193, v67
	v_exp_f32_e32 v72, v72
	v_exp_f32_e32 v73, v73
	ds_read_b128 v[200:203], v103 offset:53248
	s_waitcnt lgkmcnt(7)
	v_mfma_f32_32x32x16_bf16 v[176:191], v[108:111], v[36:39], v[176:191]
	v_exp_f32_e32 v74, v74
	v_exp_f32_e32 v75, v75
	v_exp_f32_e32 v76, v76
	v_exp_f32_e32 v77, v77
	ds_read_b128 v[108:111], v40 offset:0
	s_waitcnt lgkmcnt(7)
	v_mfma_f32_32x32x16_bf16 v[228:243], v[112:115], v[36:39], v[228:243]
	v_exp_f32_e32 v78, v78
	v_exp_f32_e32 v79, v79
	v_exp_f32_e32 v80, v80
	v_exp_f32_e32 v81, v81
	ds_read_b128 v[112:115], v41 offset:0
	s_waitcnt lgkmcnt(7)
	v_mfma_f32_32x32x16_bf16 v[176:191], v[116:119], v[84:87], v[176:191]
	v_exp_f32_e32 v82, v82
	v_exp_f32_e32 v83, v83
	v_exp_f32_e32 v132, v132
	ds_read_b128 v[116:119], v42 offset:0
	s_waitcnt lgkmcnt(7)
	v_mfma_f32_32x32x16_bf16 v[228:243], v[124:127], v[84:87], v[228:243]
	v_exp_f32_e32 v133, v133
	v_exp_f32_e32 v134, v134
	v_exp_f32_e32 v135, v135
	ds_read_b128 v[124:127], v96 offset:0
	s_waitcnt lgkmcnt(7)
	v_mfma_f32_32x32x16_bf16 v[176:191], v[148:151], v[88:91], v[176:191]
	v_exp_f32_e32 v136, v136
	v_exp_f32_e32 v137, v137
	v_exp_f32_e32 v138, v138
	ds_read_b128 v[148:151], v40 offset:4096
	s_waitcnt lgkmcnt(7)
	v_mfma_f32_32x32x16_bf16 v[228:243], v[152:155], v[88:91], v[228:243]
	v_exp_f32_e32 v139, v139
	v_exp_f32_e32 v140, v140
	v_exp_f32_e32 v141, v141
	ds_read_b128 v[152:155], v41 offset:4096
	s_waitcnt lgkmcnt(7)
	v_mfma_f32_32x32x16_bf16 v[176:191], v[156:159], v[92:95], v[176:191]
	v_exp_f32_e32 v142, v142
	v_exp_f32_e32 v143, v143
	v_exp_f32_e32 v144, v144
	ds_read_b128 v[156:159], v42 offset:4096
	s_waitcnt lgkmcnt(7)
	v_mfma_f32_32x32x16_bf16 v[228:243], v[200:203], v[92:95], v[228:243]
	v_exp_f32_e32 v145, v145
	v_exp_f32_e32 v146, v146
	v_exp_f32_e32 v147, v147
	ds_read_b128 v[200:203], v96 offset:4096
	s_cmp_eq_u32 s38, s48
	s_cbranch_scc0 .Lattn_nofix3
	v_cmp_le_i32_e64 s[50:51], 0, v120
	v_cmp_le_i32_e64 s[52:53], 1, v120
	v_cmp_le_i32_e64 s[56:57], 2, v120
	v_cndmask_b32_e64 v68, 0, v68, s[50:51]
	v_cmp_le_i32_e64 s[50:51], 3, v120
	v_cndmask_b32_e64 v69, 0, v69, s[52:53]
	v_cmp_le_i32_e64 s[52:53], 4, v120
	v_cndmask_b32_e64 v70, 0, v70, s[56:57]
	v_cmp_le_i32_e64 s[56:57], 5, v120
	v_cndmask_b32_e64 v71, 0, v71, s[50:51]
	v_cmp_le_i32_e64 s[50:51], 6, v120
	v_cndmask_b32_e64 v72, 0, v72, s[52:53]
	v_cmp_le_i32_e64 s[52:53], 7, v120
	v_cndmask_b32_e64 v73, 0, v73, s[56:57]
	v_cmp_le_i32_e64 s[56:57], 16, v120
	v_cndmask_b32_e64 v74, 0, v74, s[50:51]
	v_cmp_le_i32_e64 s[50:51], 17, v120
	v_cndmask_b32_e64 v75, 0, v75, s[52:53]
	v_cmp_le_i32_e64 s[52:53], 18, v120
	v_cndmask_b32_e64 v76, 0, v76, s[56:57]
	v_cmp_le_i32_e64 s[56:57], 19, v120
	v_cndmask_b32_e64 v77, 0, v77, s[50:51]
	v_cmp_le_i32_e64 s[50:51], 20, v120
	v_cndmask_b32_e64 v78, 0, v78, s[52:53]
	v_cmp_le_i32_e64 s[52:53], 21, v120
	v_cndmask_b32_e64 v79, 0, v79, s[56:57]
	v_cmp_le_i32_e64 s[56:57], 22, v120
	v_cndmask_b32_e64 v80, 0, v80, s[50:51]
	v_cmp_le_i32_e64 s[50:51], 23, v120
	v_cndmask_b32_e64 v81, 0, v81, s[52:53]
	v_cmp_le_i32_e64 s[52:53], 32, v120
	v_cndmask_b32_e64 v82, 0, v82, s[56:57]
	v_cmp_le_i32_e64 s[56:57], 33, v120
	v_cndmask_b32_e64 v83, 0, v83, s[50:51]
	v_cmp_le_i32_e64 s[50:51], 34, v120
	v_cndmask_b32_e64 v132, 0, v132, s[52:53]
	v_cmp_le_i32_e64 s[52:53], 35, v120
	v_cndmask_b32_e64 v133, 0, v133, s[56:57]
	v_cmp_le_i32_e64 s[56:57], 36, v120
	v_cndmask_b32_e64 v134, 0, v134, s[50:51]
	v_cmp_le_i32_e64 s[50:51], 37, v120
	v_cndmask_b32_e64 v135, 0, v135, s[52:53]
	v_cmp_le_i32_e64 s[52:53], 38, v120
	v_cndmask_b32_e64 v136, 0, v136, s[56:57]
	v_cmp_le_i32_e64 s[56:57], 39, v120
	v_cndmask_b32_e64 v137, 0, v137, s[50:51]
	v_cmp_le_i32_e64 s[50:51], 48, v120
	v_cndmask_b32_e64 v138, 0, v138, s[52:53]
	v_cmp_le_i32_e64 s[52:53], 49, v120
	v_cndmask_b32_e64 v139, 0, v139, s[56:57]
	v_cmp_le_i32_e64 s[56:57], 50, v120
	v_cndmask_b32_e64 v140, 0, v140, s[50:51]
	v_cmp_le_i32_e64 s[50:51], 51, v120
	v_cndmask_b32_e64 v141, 0, v141, s[52:53]
	v_cmp_le_i32_e64 s[52:53], 52, v120
	v_cndmask_b32_e64 v142, 0, v142, s[56:57]
	v_cmp_le_i32_e64 s[56:57], 53, v120
	v_cndmask_b32_e64 v143, 0, v143, s[50:51]
	v_cmp_le_i32_e64 s[50:51], 54, v120
	v_cndmask_b32_e64 v144, 0, v144, s[52:53]
	v_cmp_le_i32_e64 s[52:53], 55, v120
	v_cndmask_b32_e64 v145, 0, v145, s[56:57]
	s_nop 0
	v_cndmask_b32_e64 v146, 0, v146, s[50:51]
	s_nop 0
	v_cndmask_b32_e64 v147, 0, v147, s[52:53]
	s_nop 0
